# LRU unit staging rewritten by hand (pk_fma conv, unconditional loads, masked LDS writes) + next-unit load prefetch before mt loop
# speedup vs baseline: 1.1298x; 1.0095x over previous
.LBB0_347:
	v_mov_b32_e32 v161, v184
	s_lshl_b32 s0, s31, 7
	s_and_b32 s5, s0, 0x380
	s_ashr_i32 s35, s31, 6
	s_mul_i32 s0, s35, 0x81
	s_ashr_i32 s1, s0, 3
	s_addk_i32 s0, 0x81
	s_ashr_i32 s0, s0, 3
	s_sub_i32 s68, s0, s1
	s_lshl_b32 s4, s1, 4
	s_lshl_b32 s7, s68, 4
	s_bfe_u32 s34, s31, 0x30003
	s_mul_i32 s6, s34, 0x810
	v_and_b32_e32 v0, 15, v161
	v_lshrrev_b32_e32 v1, 4, v161
	v_mul_u32_u24_e32 v4, 9, v1
	v_sub_u32_e32 v5, s7, v4
	v_med3_i32 v5, v5, 0, 9
	v_mul_u32_u24_e32 v56, 0x990, v1
	v_lshl_add_u32 v56, v0, 4, v56
	v_mul_u32_u24_e32 v57, 0x900, v1
	v_lshl_add_u32 v57, v0, 4, v57
	v_add_u32_e32 v57, s19, v57
	v_readlane_b32 s0, v250, 0
	s_cmp_lg_u32 s31, s0
	s_cbranch_scc1 .Lstg_prefetched
	s_add_i32 s0, s6, s4
	v_lshl_add_u32 v2, v0, 3, s5
	v_lshlrev_b32_e32 v3, 2, v2
	v_add_u32_e32 v58, 0x1000, v3
	v_add_u32_e32 v59, 0x2000, v3
	v_add_u32_e32 v60, 0x3000, v3
	v_add_u32_e32 v6, s0, v4
	v_mul_u32_u24_e32 v7, 0x1c00, v6
	v_lshl_add_u32 v7, v2, 1, v7
	global_load_dwordx4 v[68:71], v3, s[64:65]
	global_load_dwordx4 v[72:75], v3, s[64:65] offset:16
	global_load_dwordx4 v[76:79], v58, s[64:65]
	global_load_dwordx4 v[80:83], v58, s[64:65] offset:16
	global_load_dwordx4 v[84:87], v59, s[64:65]
	global_load_dwordx4 v[88:91], v59, s[64:65] offset:16
	global_load_dwordx4 v[92:95], v60, s[64:65]
	global_load_dwordx4 v[96:99], v60, s[64:65] offset:16
	global_load_dwordx4 v[100:103], v3, s[66:67]
	global_load_dwordx4 v[104:107], v3, s[66:67] offset:16
	s_sub_u32 s40, s56, 0x5400
	s_subb_u32 s41, s57, 0
	global_load_dwordx4 v[108:111], v7, s[40:41]
	s_add_u32 s40, s40, 0x1c00
	s_addc_u32 s41, s41, 0
	global_load_dwordx4 v[112:115], v7, s[40:41]
	s_add_u32 s40, s40, 0x1c00
	s_addc_u32 s41, s41, 0
	global_load_dwordx4 v[116:119], v7, s[40:41]
	s_add_u32 s40, s40, 0x1c00
	s_addc_u32 s41, s41, 0
	global_load_dwordx4 v[120:123], v7, s[40:41]
	s_add_u32 s40, s40, 0x1c00
	s_addc_u32 s41, s41, 0
	global_load_dwordx4 v[128:131], v7, s[40:41]
	s_add_u32 s40, s40, 0x1c00
	s_addc_u32 s41, s41, 0
	global_load_dwordx4 v[132:135], v7, s[40:41]
	s_add_u32 s40, s40, 0x1c00
	s_addc_u32 s41, s41, 0
	global_load_dwordx4 v[136:139], v7, s[40:41]
	s_add_u32 s40, s40, 0x1c00
	s_addc_u32 s41, s41, 0
	global_load_dwordx4 v[140:143], v7, s[40:41]
	s_add_u32 s40, s40, 0x1c00
	s_addc_u32 s41, s41, 0
	global_load_dwordx4 v[144:147], v7, s[40:41]
	s_add_u32 s40, s40, 0x1c00
	s_addc_u32 s41, s41, 0
	global_load_dwordx4 v[148:151], v7, s[40:41]
	s_add_u32 s40, s40, 0x1c00
	s_addc_u32 s41, s41, 0
	global_load_dwordx4 v[152:155], v7, s[40:41]
	s_add_u32 s40, s40, 0x1c00
	s_addc_u32 s41, s41, 0
	global_load_dwordx4 v[162:165], v7, s[40:41]
	s_add_u32 s40, s56, 0xc00
	s_addc_u32 s41, s57, 0
	global_load_dwordx4 v[172:175], v7, s[40:41]
	s_add_u32 s40, s40, 0x1c00
	s_addc_u32 s41, s41, 0
	global_load_dwordx4 v[176:179], v7, s[40:41]
	s_add_u32 s40, s40, 0x1c00
	s_addc_u32 s41, s41, 0
	global_load_dwordx4 v[180:183], v7, s[40:41]
	s_add_u32 s40, s40, 0x1c00
	s_addc_u32 s41, s41, 0
	global_load_dwordx4 v[188:191], v7, s[40:41]
	s_add_u32 s40, s40, 0x1c00
	s_addc_u32 s41, s41, 0
	global_load_dwordx4 v[192:195], v7, s[40:41]
	s_add_u32 s40, s40, 0x1c00
	s_addc_u32 s41, s41, 0
	global_load_dwordx4 v[196:199], v7, s[40:41]
	s_add_u32 s40, s40, 0x1c00
	s_addc_u32 s41, s41, 0
	global_load_dwordx4 v[200:203], v7, s[40:41]
	s_add_u32 s40, s40, 0x1c00
	s_addc_u32 s41, s41, 0
	global_load_dwordx4 v[204:207], v7, s[40:41]
	s_add_u32 s40, s40, 0x1c00
	s_addc_u32 s41, s41, 0
	global_load_dwordx4 v[208:211], v7, s[40:41]
	s_branch .Lstg_go

.Lstg_go:
	s_waitcnt vmcnt(18)
	s_cmp_lg_u32 s4, 0
	s_cbranch_scc1 .Lstg_nopad
	v_cmp_eq_u32_e32 vcc, 0, v1
	s_nop 1
	v_cndmask_b32_e64 v108, v108, 0, vcc
	v_cndmask_b32_e64 v109, v109, 0, vcc
	v_cndmask_b32_e64 v110, v110, 0, vcc
	v_cndmask_b32_e64 v111, v111, 0, vcc
	v_cndmask_b32_e64 v112, v112, 0, vcc
	v_cndmask_b32_e64 v113, v113, 0, vcc
	v_cndmask_b32_e64 v114, v114, 0, vcc
	v_cndmask_b32_e64 v115, v115, 0, vcc
	v_cndmask_b32_e64 v116, v116, 0, vcc
	v_cndmask_b32_e64 v117, v117, 0, vcc
	v_cndmask_b32_e64 v118, v118, 0, vcc
	v_cndmask_b32_e64 v119, v119, 0, vcc
.Lstg_nopad:
	v_lshlrev_b32_e32 v8, 16, v108
	v_and_b32_e32 v9, 0xffff0000, v108
	v_lshlrev_b32_e32 v10, 16, v109
	v_and_b32_e32 v11, 0xffff0000, v109
	v_lshlrev_b32_e32 v12, 16, v110
	v_and_b32_e32 v13, 0xffff0000, v110
	v_lshlrev_b32_e32 v14, 16, v111
	v_and_b32_e32 v15, 0xffff0000, v111
	v_lshlrev_b32_e32 v16, 16, v112
	v_and_b32_e32 v17, 0xffff0000, v112
	v_lshlrev_b32_e32 v18, 16, v113
	v_and_b32_e32 v19, 0xffff0000, v113
	v_lshlrev_b32_e32 v20, 16, v114
	v_and_b32_e32 v21, 0xffff0000, v114
	v_lshlrev_b32_e32 v22, 16, v115
	v_and_b32_e32 v23, 0xffff0000, v115
	v_lshlrev_b32_e32 v24, 16, v116
	v_and_b32_e32 v25, 0xffff0000, v116
	v_lshlrev_b32_e32 v26, 16, v117
	v_and_b32_e32 v27, 0xffff0000, v117
	v_lshlrev_b32_e32 v28, 16, v118
	v_and_b32_e32 v29, 0xffff0000, v118
	v_lshlrev_b32_e32 v30, 16, v119
	v_and_b32_e32 v31, 0xffff0000, v119
	s_waitcnt vmcnt(17)
	v_lshlrev_b32_e32 v32, 16, v120
	v_and_b32_e32 v33, 0xffff0000, v120
	v_lshlrev_b32_e32 v34, 16, v121
	v_and_b32_e32 v35, 0xffff0000, v121
	v_lshlrev_b32_e32 v36, 16, v122
	v_and_b32_e32 v37, 0xffff0000, v122
	v_lshlrev_b32_e32 v38, 16, v123
	v_and_b32_e32 v39, 0xffff0000, v123
	v_pk_fma_f32 v[40:41], v[68:69], v[8:9], v[100:101]
	v_pk_fma_f32 v[42:43], v[70:71], v[10:11], v[102:103]
	v_pk_fma_f32 v[44:45], v[72:73], v[12:13], v[104:105]
	v_pk_fma_f32 v[46:47], v[74:75], v[14:15], v[106:107]
	v_pk_fma_f32 v[40:41], v[76:77], v[16:17], v[40:41]
	v_pk_fma_f32 v[42:43], v[78:79], v[18:19], v[42:43]
	v_pk_fma_f32 v[44:45], v[80:81], v[20:21], v[44:45]
	v_pk_fma_f32 v[46:47], v[82:83], v[22:23], v[46:47]
	v_pk_fma_f32 v[40:41], v[84:85], v[24:25], v[40:41]
	v_pk_fma_f32 v[42:43], v[86:87], v[26:27], v[42:43]
	v_pk_fma_f32 v[44:45], v[88:89], v[28:29], v[44:45]
	v_pk_fma_f32 v[46:47], v[90:91], v[30:31], v[46:47]
	v_pk_fma_f32 v[40:41], v[92:93], v[32:33], v[40:41]
	v_pk_fma_f32 v[42:43], v[94:95], v[34:35], v[42:43]
	v_pk_fma_f32 v[44:45], v[96:97], v[36:37], v[44:45]
	v_pk_fma_f32 v[46:47], v[98:99], v[38:39], v[46:47]
	v_cmp_lt_u32_e32 vcc, 0, v5
	v_cvt_pk_bf16_f32 v48, v40, v41
	v_cvt_pk_bf16_f32 v49, v42, v43
	v_cvt_pk_bf16_f32 v50, v44, v45
	v_cvt_pk_bf16_f32 v51, v46, v47
	s_and_saveexec_b64 s[0:1], vcc
	ds_write_b128 v56, v[48:51]
	s_mov_b64 exec, s[0:1]
	s_waitcnt vmcnt(16)
	v_lshlrev_b32_e32 v8, 16, v128
	v_and_b32_e32 v9, 0xffff0000, v128
	v_lshlrev_b32_e32 v10, 16, v129
	v_and_b32_e32 v11, 0xffff0000, v129
	v_lshlrev_b32_e32 v12, 16, v130
	v_and_b32_e32 v13, 0xffff0000, v130
	v_lshlrev_b32_e32 v14, 16, v131
	v_and_b32_e32 v15, 0xffff0000, v131
	v_pk_fma_f32 v[40:41], v[68:69], v[16:17], v[100:101]
	v_pk_fma_f32 v[42:43], v[70:71], v[18:19], v[102:103]
	v_pk_fma_f32 v[44:45], v[72:73], v[20:21], v[104:105]
	v_pk_fma_f32 v[46:47], v[74:75], v[22:23], v[106:107]
	v_pk_fma_f32 v[40:41], v[76:77], v[24:25], v[40:41]
	v_pk_fma_f32 v[42:43], v[78:79], v[26:27], v[42:43]
	v_pk_fma_f32 v[44:45], v[80:81], v[28:29], v[44:45]
	v_pk_fma_f32 v[46:47], v[82:83], v[30:31], v[46:47]
	v_pk_fma_f32 v[40:41], v[84:85], v[32:33], v[40:41]
	v_pk_fma_f32 v[42:43], v[86:87], v[34:35], v[42:43]
	v_pk_fma_f32 v[44:45], v[88:89], v[36:37], v[44:45]
	v_pk_fma_f32 v[46:47], v[90:91], v[38:39], v[46:47]
	v_pk_fma_f32 v[40:41], v[92:93], v[8:9], v[40:41]
	v_pk_fma_f32 v[42:43], v[94:95], v[10:11], v[42:43]
	v_pk_fma_f32 v[44:45], v[96:97], v[12:13], v[44:45]
	v_pk_fma_f32 v[46:47], v[98:99], v[14:15], v[46:47]
	v_cmp_lt_u32_e32 vcc, 1, v5
	v_cvt_pk_bf16_f32 v52, v40, v41
	v_cvt_pk_bf16_f32 v53, v42, v43
	v_cvt_pk_bf16_f32 v54, v44, v45
	v_cvt_pk_bf16_f32 v55, v46, v47
	s_and_saveexec_b64 s[0:1], vcc
	ds_write_b128 v56, v[52:55] offset:272
	s_mov_b64 exec, s[0:1]
	s_waitcnt vmcnt(15)
	v_lshlrev_b32_e32 v16, 16, v132
	v_and_b32_e32 v17, 0xffff0000, v132
	v_lshlrev_b32_e32 v18, 16, v133
	v_and_b32_e32 v19, 0xffff0000, v133
	v_lshlrev_b32_e32 v20, 16, v134
	v_and_b32_e32 v21, 0xffff0000, v134
	v_lshlrev_b32_e32 v22, 16, v135
	v_and_b32_e32 v23, 0xffff0000, v135
	v_pk_fma_f32 v[40:41], v[68:69], v[24:25], v[100:101]
	v_pk_fma_f32 v[42:43], v[70:71], v[26:27], v[102:103]
	v_pk_fma_f32 v[44:45], v[72:73], v[28:29], v[104:105]
	v_pk_fma_f32 v[46:47], v[74:75], v[30:31], v[106:107]
	v_pk_fma_f32 v[40:41], v[76:77], v[32:33], v[40:41]
	v_pk_fma_f32 v[42:43], v[78:79], v[34:35], v[42:43]
	v_pk_fma_f32 v[44:45], v[80:81], v[36:37], v[44:45]
	v_pk_fma_f32 v[46:47], v[82:83], v[38:39], v[46:47]
	v_pk_fma_f32 v[40:41], v[84:85], v[8:9], v[40:41]
	v_pk_fma_f32 v[42:43], v[86:87], v[10:11], v[42:43]
	v_pk_fma_f32 v[44:45], v[88:89], v[12:13], v[44:45]
	v_pk_fma_f32 v[46:47], v[90:91], v[14:15], v[46:47]
	v_pk_fma_f32 v[40:41], v[92:93], v[16:17], v[40:41]
	v_pk_fma_f32 v[42:43], v[94:95], v[18:19], v[42:43]
	v_pk_fma_f32 v[44:45], v[96:97], v[20:21], v[44:45]
	v_pk_fma_f32 v[46:47], v[98:99], v[22:23], v[46:47]
	v_cmp_lt_u32_e32 vcc, 2, v5
	v_cvt_pk_bf16_f32 v48, v40, v41
	v_cvt_pk_bf16_f32 v49, v42, v43
	v_cvt_pk_bf16_f32 v50, v44, v45
	v_cvt_pk_bf16_f32 v51, v46, v47
	s_and_saveexec_b64 s[0:1], vcc
	ds_write_b128 v56, v[48:51] offset:544
	s_mov_b64 exec, s[0:1]
	s_waitcnt vmcnt(14)
	v_lshlrev_b32_e32 v24, 16, v136
	v_and_b32_e32 v25, 0xffff0000, v136
	v_lshlrev_b32_e32 v26, 16, v137
	v_and_b32_e32 v27, 0xffff0000, v137
	v_lshlrev_b32_e32 v28, 16, v138
	v_and_b32_e32 v29, 0xffff0000, v138
	v_lshlrev_b32_e32 v30, 16, v139
	v_and_b32_e32 v31, 0xffff0000, v139
	v_pk_fma_f32 v[40:41], v[68:69], v[32:33], v[100:101]
	v_pk_fma_f32 v[42:43], v[70:71], v[34:35], v[102:103]
	v_pk_fma_f32 v[44:45], v[72:73], v[36:37], v[104:105]
	v_pk_fma_f32 v[46:47], v[74:75], v[38:39], v[106:107]
	v_pk_fma_f32 v[40:41], v[76:77], v[8:9], v[40:41]
	v_pk_fma_f32 v[42:43], v[78:79], v[10:11], v[42:43]
	v_pk_fma_f32 v[44:45], v[80:81], v[12:13], v[44:45]
	v_pk_fma_f32 v[46:47], v[82:83], v[14:15], v[46:47]
	v_pk_fma_f32 v[40:41], v[84:85], v[16:17], v[40:41]
	v_pk_fma_f32 v[42:43], v[86:87], v[18:19], v[42:43]
	v_pk_fma_f32 v[44:45], v[88:89], v[20:21], v[44:45]
	v_pk_fma_f32 v[46:47], v[90:91], v[22:23], v[46:47]
	v_pk_fma_f32 v[40:41], v[92:93], v[24:25], v[40:41]
	v_pk_fma_f32 v[42:43], v[94:95], v[26:27], v[42:43]
	v_pk_fma_f32 v[44:45], v[96:97], v[28:29], v[44:45]
	v_pk_fma_f32 v[46:47], v[98:99], v[30:31], v[46:47]
	v_cmp_lt_u32_e32 vcc, 3, v5
	v_cvt_pk_bf16_f32 v52, v40, v41
	v_cvt_pk_bf16_f32 v53, v42, v43
	v_cvt_pk_bf16_f32 v54, v44, v45
	v_cvt_pk_bf16_f32 v55, v46, v47
	s_and_saveexec_b64 s[0:1], vcc
	ds_write_b128 v56, v[52:55] offset:816
	s_mov_b64 exec, s[0:1]
	s_waitcnt vmcnt(13)
	v_lshlrev_b32_e32 v32, 16, v140
	v_and_b32_e32 v33, 0xffff0000, v140
	v_lshlrev_b32_e32 v34, 16, v141
	v_and_b32_e32 v35, 0xffff0000, v141
	v_lshlrev_b32_e32 v36, 16, v142
	v_and_b32_e32 v37, 0xffff0000, v142
	v_lshlrev_b32_e32 v38, 16, v143
	v_and_b32_e32 v39, 0xffff0000, v143
	v_pk_fma_f32 v[40:41], v[68:69], v[8:9], v[100:101]
	v_pk_fma_f32 v[42:43], v[70:71], v[10:11], v[102:103]
	v_pk_fma_f32 v[44:45], v[72:73], v[12:13], v[104:105]
	v_pk_fma_f32 v[46:47], v[74:75], v[14:15], v[106:107]
	v_pk_fma_f32 v[40:41], v[76:77], v[16:17], v[40:41]
	v_pk_fma_f32 v[42:43], v[78:79], v[18:19], v[42:43]
	v_pk_fma_f32 v[44:45], v[80:81], v[20:21], v[44:45]
	v_pk_fma_f32 v[46:47], v[82:83], v[22:23], v[46:47]
	v_pk_fma_f32 v[40:41], v[84:85], v[24:25], v[40:41]
	v_pk_fma_f32 v[42:43], v[86:87], v[26:27], v[42:43]
	v_pk_fma_f32 v[44:45], v[88:89], v[28:29], v[44:45]
	v_pk_fma_f32 v[46:47], v[90:91], v[30:31], v[46:47]
	v_pk_fma_f32 v[40:41], v[92:93], v[32:33], v[40:41]
	v_pk_fma_f32 v[42:43], v[94:95], v[34:35], v[42:43]
	v_pk_fma_f32 v[44:45], v[96:97], v[36:37], v[44:45]
	v_pk_fma_f32 v[46:47], v[98:99], v[38:39], v[46:47]
	v_cmp_lt_u32_e32 vcc, 4, v5
	v_cvt_pk_bf16_f32 v48, v40, v41
	v_cvt_pk_bf16_f32 v49, v42, v43
	v_cvt_pk_bf16_f32 v50, v44, v45
	v_cvt_pk_bf16_f32 v51, v46, v47
	s_and_saveexec_b64 s[0:1], vcc
	ds_write_b128 v56, v[48:51] offset:1088
	s_mov_b64 exec, s[0:1]
	s_waitcnt vmcnt(12)
	v_lshlrev_b32_e32 v8, 16, v144
	v_and_b32_e32 v9, 0xffff0000, v144
	v_lshlrev_b32_e32 v10, 16, v145
	v_and_b32_e32 v11, 0xffff0000, v145
	v_lshlrev_b32_e32 v12, 16, v146
	v_and_b32_e32 v13, 0xffff0000, v146
	v_lshlrev_b32_e32 v14, 16, v147
	v_and_b32_e32 v15, 0xffff0000, v147
	v_pk_fma_f32 v[40:41], v[68:69], v[16:17], v[100:101]
	v_pk_fma_f32 v[42:43], v[70:71], v[18:19], v[102:103]
	v_pk_fma_f32 v[44:45], v[72:73], v[20:21], v[104:105]
	v_pk_fma_f32 v[46:47], v[74:75], v[22:23], v[106:107]
	v_pk_fma_f32 v[40:41], v[76:77], v[24:25], v[40:41]
	v_pk_fma_f32 v[42:43], v[78:79], v[26:27], v[42:43]
	v_pk_fma_f32 v[44:45], v[80:81], v[28:29], v[44:45]
	v_pk_fma_f32 v[46:47], v[82:83], v[30:31], v[46:47]
	v_pk_fma_f32 v[40:41], v[84:85], v[32:33], v[40:41]
	v_pk_fma_f32 v[42:43], v[86:87], v[34:35], v[42:43]
	v_pk_fma_f32 v[44:45], v[88:89], v[36:37], v[44:45]
	v_pk_fma_f32 v[46:47], v[90:91], v[38:39], v[46:47]
	v_pk_fma_f32 v[40:41], v[92:93], v[8:9], v[40:41]
	v_pk_fma_f32 v[42:43], v[94:95], v[10:11], v[42:43]
	v_pk_fma_f32 v[44:45], v[96:97], v[12:13], v[44:45]
	v_pk_fma_f32 v[46:47], v[98:99], v[14:15], v[46:47]
	v_cmp_lt_u32_e32 vcc, 5, v5
	v_cvt_pk_bf16_f32 v52, v40, v41
	v_cvt_pk_bf16_f32 v53, v42, v43
	v_cvt_pk_bf16_f32 v54, v44, v45
	v_cvt_pk_bf16_f32 v55, v46, v47
	s_and_saveexec_b64 s[0:1], vcc
	ds_write_b128 v56, v[52:55] offset:1360
	s_mov_b64 exec, s[0:1]
	s_waitcnt vmcnt(11)
	v_lshlrev_b32_e32 v16, 16, v148
	v_and_b32_e32 v17, 0xffff0000, v148
	v_lshlrev_b32_e32 v18, 16, v149
	v_and_b32_e32 v19, 0xffff0000, v149
	v_lshlrev_b32_e32 v20, 16, v150
	v_and_b32_e32 v21, 0xffff0000, v150
	v_lshlrev_b32_e32 v22, 16, v151
	v_and_b32_e32 v23, 0xffff0000, v151
	v_pk_fma_f32 v[40:41], v[68:69], v[24:25], v[100:101]
	v_pk_fma_f32 v[42:43], v[70:71], v[26:27], v[102:103]
	v_pk_fma_f32 v[44:45], v[72:73], v[28:29], v[104:105]
	v_pk_fma_f32 v[46:47], v[74:75], v[30:31], v[106:107]
	v_pk_fma_f32 v[40:41], v[76:77], v[32:33], v[40:41]
	v_pk_fma_f32 v[42:43], v[78:79], v[34:35], v[42:43]
	v_pk_fma_f32 v[44:45], v[80:81], v[36:37], v[44:45]
	v_pk_fma_f32 v[46:47], v[82:83], v[38:39], v[46:47]
	v_pk_fma_f32 v[40:41], v[84:85], v[8:9], v[40:41]
	v_pk_fma_f32 v[42:43], v[86:87], v[10:11], v[42:43]
	v_pk_fma_f32 v[44:45], v[88:89], v[12:13], v[44:45]
	v_pk_fma_f32 v[46:47], v[90:91], v[14:15], v[46:47]
	v_pk_fma_f32 v[40:41], v[92:93], v[16:17], v[40:41]
	v_pk_fma_f32 v[42:43], v[94:95], v[18:19], v[42:43]
	v_pk_fma_f32 v[44:45], v[96:97], v[20:21], v[44:45]
	v_pk_fma_f32 v[46:47], v[98:99], v[22:23], v[46:47]
	v_cmp_lt_u32_e32 vcc, 6, v5
	v_cvt_pk_bf16_f32 v48, v40, v41
	v_cvt_pk_bf16_f32 v49, v42, v43
	v_cvt_pk_bf16_f32 v50, v44, v45
	v_cvt_pk_bf16_f32 v51, v46, v47
	s_and_saveexec_b64 s[0:1], vcc
	ds_write_b128 v56, v[48:51] offset:1632
	s_mov_b64 exec, s[0:1]
	s_waitcnt vmcnt(10)
	v_lshlrev_b32_e32 v24, 16, v152
	v_and_b32_e32 v25, 0xffff0000, v152
	v_lshlrev_b32_e32 v26, 16, v153
	v_and_b32_e32 v27, 0xffff0000, v153
	v_lshlrev_b32_e32 v28, 16, v154
	v_and_b32_e32 v29, 0xffff0000, v154
	v_lshlrev_b32_e32 v30, 16, v155
	v_and_b32_e32 v31, 0xffff0000, v155
	v_pk_fma_f32 v[40:41], v[68:69], v[32:33], v[100:101]
	v_pk_fma_f32 v[42:43], v[70:71], v[34:35], v[102:103]
	v_pk_fma_f32 v[44:45], v[72:73], v[36:37], v[104:105]
	v_pk_fma_f32 v[46:47], v[74:75], v[38:39], v[106:107]
	v_pk_fma_f32 v[40:41], v[76:77], v[8:9], v[40:41]
	v_pk_fma_f32 v[42:43], v[78:79], v[10:11], v[42:43]
	v_pk_fma_f32 v[44:45], v[80:81], v[12:13], v[44:45]
	v_pk_fma_f32 v[46:47], v[82:83], v[14:15], v[46:47]
	v_pk_fma_f32 v[40:41], v[84:85], v[16:17], v[40:41]
	v_pk_fma_f32 v[42:43], v[86:87], v[18:19], v[42:43]
	v_pk_fma_f32 v[44:45], v[88:89], v[20:21], v[44:45]
	v_pk_fma_f32 v[46:47], v[90:91], v[22:23], v[46:47]
	v_pk_fma_f32 v[40:41], v[92:93], v[24:25], v[40:41]
	v_pk_fma_f32 v[42:43], v[94:95], v[26:27], v[42:43]
	v_pk_fma_f32 v[44:45], v[96:97], v[28:29], v[44:45]
	v_pk_fma_f32 v[46:47], v[98:99], v[30:31], v[46:47]
	v_cmp_lt_u32_e32 vcc, 7, v5
	v_cvt_pk_bf16_f32 v52, v40, v41
	v_cvt_pk_bf16_f32 v53, v42, v43
	v_cvt_pk_bf16_f32 v54, v44, v45
	v_cvt_pk_bf16_f32 v55, v46, v47
	s_and_saveexec_b64 s[0:1], vcc
	ds_write_b128 v56, v[52:55] offset:1904
	s_mov_b64 exec, s[0:1]
	s_waitcnt vmcnt(9)
	v_lshlrev_b32_e32 v32, 16, v162
	v_and_b32_e32 v33, 0xffff0000, v162
	v_lshlrev_b32_e32 v34, 16, v163
	v_and_b32_e32 v35, 0xffff0000, v163
	v_lshlrev_b32_e32 v36, 16, v164
	v_and_b32_e32 v37, 0xffff0000, v164
	v_lshlrev_b32_e32 v38, 16, v165
	v_and_b32_e32 v39, 0xffff0000, v165
	v_pk_fma_f32 v[40:41], v[68:69], v[8:9], v[100:101]
	v_pk_fma_f32 v[42:43], v[70:71], v[10:11], v[102:103]
	v_pk_fma_f32 v[44:45], v[72:73], v[12:13], v[104:105]
	v_pk_fma_f32 v[46:47], v[74:75], v[14:15], v[106:107]
	v_pk_fma_f32 v[40:41], v[76:77], v[16:17], v[40:41]
	v_pk_fma_f32 v[42:43], v[78:79], v[18:19], v[42:43]
	v_pk_fma_f32 v[44:45], v[80:81], v[20:21], v[44:45]
	v_pk_fma_f32 v[46:47], v[82:83], v[22:23], v[46:47]
	v_pk_fma_f32 v[40:41], v[84:85], v[24:25], v[40:41]
	v_pk_fma_f32 v[42:43], v[86:87], v[26:27], v[42:43]
	v_pk_fma_f32 v[44:45], v[88:89], v[28:29], v[44:45]
	v_pk_fma_f32 v[46:47], v[90:91], v[30:31], v[46:47]
	v_pk_fma_f32 v[40:41], v[92:93], v[32:33], v[40:41]
	v_pk_fma_f32 v[42:43], v[94:95], v[34:35], v[42:43]
	v_pk_fma_f32 v[44:45], v[96:97], v[36:37], v[44:45]
	v_pk_fma_f32 v[46:47], v[98:99], v[38:39], v[46:47]
	v_cmp_lt_u32_e32 vcc, 8, v5
	v_cvt_pk_bf16_f32 v48, v40, v41
	v_cvt_pk_bf16_f32 v49, v42, v43
	v_cvt_pk_bf16_f32 v50, v44, v45
	v_cvt_pk_bf16_f32 v51, v46, v47
	s_and_saveexec_b64 s[0:1], vcc
	ds_write_b128 v56, v[48:51] offset:2176
	s_mov_b64 exec, s[0:1]
	s_waitcnt vmcnt(0)
	v_cmp_lt_u32_e32 vcc, 0, v5
	s_and_saveexec_b64 s[0:1], vcc
	ds_write_b128 v57, v[172:175]
	s_mov_b64 exec, s[0:1]
	v_cmp_lt_u32_e32 vcc, 1, v5
	s_and_saveexec_b64 s[0:1], vcc
	ds_write_b128 v57, v[176:179] offset:256
	s_mov_b64 exec, s[0:1]
	v_cmp_lt_u32_e32 vcc, 2, v5
	s_and_saveexec_b64 s[0:1], vcc
	ds_write_b128 v57, v[180:183] offset:512
	s_mov_b64 exec, s[0:1]
	v_cmp_lt_u32_e32 vcc, 3, v5
	s_and_saveexec_b64 s[0:1], vcc
	ds_write_b128 v57, v[188:191] offset:768
	s_mov_b64 exec, s[0:1]
	v_cmp_lt_u32_e32 vcc, 4, v5
	s_and_saveexec_b64 s[0:1], vcc
	ds_write_b128 v57, v[192:195] offset:1024
	s_mov_b64 exec, s[0:1]
	v_cmp_lt_u32_e32 vcc, 5, v5
	s_and_saveexec_b64 s[0:1], vcc
	ds_write_b128 v57, v[196:199] offset:1280
	s_mov_b64 exec, s[0:1]
	v_cmp_lt_u32_e32 vcc, 6, v5
	s_and_saveexec_b64 s[0:1], vcc
	ds_write_b128 v57, v[200:203] offset:1536
	s_mov_b64 exec, s[0:1]
	v_cmp_lt_u32_e32 vcc, 7, v5
	s_and_saveexec_b64 s[0:1], vcc
	ds_write_b128 v57, v[204:207] offset:1792
	s_mov_b64 exec, s[0:1]
	v_cmp_lt_u32_e32 vcc, 8, v5
	s_and_saveexec_b64 s[0:1], vcc
	ds_write_b128 v57, v[208:211] offset:2048
	s_mov_b64 exec, s[0:1]
.LBB0_407:
	v_ashrrev_i32_e32 v36, 2, v161
	v_and_b32_e32 v0, -16, v36
	v_and_b32_e32 v35, 15, v161
	v_add_u32_e32 v0, s5, v0
	v_bfe_u32 v42, v161, 4, 2
	v_or_b32_e32 v32, v0, v35
	v_ashrrev_i32_e32 v33, 31, v32
	s_cmp_lt_i32 s68, 1
	v_cmp_eq_u32_e32 vcc, 0, v42
	s_waitcnt lgkmcnt(0)
	s_barrier
	s_cbranch_scc1 .LBB0_411
	v_readlane_b32 s40, v250, 7
	v_readlane_b32 s41, v250, 8
	v_readlane_b32 s44, v250, 11
	v_readlane_b32 s45, v250, 12
	v_lshlrev_b64 v[0:1], 2, v[32:33]
	s_mov_b64 s[40:41], s[44:45]
	v_lshl_add_u64 v[2:3], s[40:41], 0, v[0:1]
	global_load_dword v37, v[2:3], off
	s_lshr_b32 s0, s31, 3
	v_add_u32_e32 v8, -16, v159
	v_and_b32_e32 v40, 64, v159
	s_and_b32 s6, s0, 7
	v_cmp_lt_i32_e64 s[0:1], v8, v40
	v_readlane_b32 s42, v250, 9
	v_readlane_b32 s43, v250, 10
	v_cndmask_b32_e64 v8, v8, v159, s[0:1]
	s_mov_b32 s0, 0xbfb8aa3b
	v_lshlrev_b64 v[2:3], 8, v[32:33]
	s_mov_b64 s[38:39], s[42:43]
	v_lshlrev_b32_e32 v124, 4, v42
	v_lshl_add_u64 v[4:5], s[14:15], 0, v[2:3]
	v_lshl_add_u64 v[2:3], s[24:25], 0, v[2:3]
	v_lshl_add_u64 v[6:7], s[70:71], 0, v[0:1]
	v_lshl_add_u64 v[0:1], s[38:39], 0, v[0:1]
	v_lshl_add_u64 v[20:21], v[4:5], 0, v[124:125]
	v_lshl_add_u64 v[28:29], v[2:3], 0, v[124:125]
	global_load_dword v45, v[6:7], off
	global_load_dword v46, v[0:1], off
	v_lshlrev_b32_e32 v47, 2, v8
	global_load_dwordx4 v[0:3], v[20:21], off
	global_load_dwordx4 v[4:7], v[20:21], off offset:64
	global_load_dwordx4 v[8:11], v[28:29], off
	global_load_dwordx4 v[12:15], v[28:29], off offset:64
	v_lshlrev_b32_e32 v36, 1, v36
	s_mulk_i32 s6, 0x810
	v_and_b32_e32 v36, 0xffffffe0, v36
	v_lshlrev_b32_e32 v34, 2, v42
	s_add_i32 s6, s6, s4
	v_mov_b32_e32 v44, 0
	v_mov_b32_e32 v43, 1.0
	s_mov_b32 s5, 0
	v_add3_u32 v34, s6, 3, v34
	v_add_u32_e32 v170, -3, v34
	v_lshl_add_u32 v170, v170, 10, v32
	v_lshlrev_b32_e32 v170, 1, v170
	v_add_u32_e32 v171, 0x1000, v170
	v_readlane_b32 s46, v250, 13
	v_readlane_b32 s47, v250, 14
	v_readlane_b32 s48, v250, 15
	v_readlane_b32 s49, v250, 16
	v_readlane_b32 s50, v250, 17
	v_readlane_b32 s51, v250, 18
	v_readlane_b32 s52, v250, 19
	v_readlane_b32 s53, v250, 20
	v_readlane_b32 s54, v250, 21
	v_readlane_b32 s55, v250, 22
	s_waitcnt vmcnt(6)
	v_mul_f32_e32 v16, 0xbfb8aa3b, v37
	v_fma_f32 v17, v37, s0, -v16
	v_rndne_f32_e32 v18, v16
	v_fmac_f32_e32 v17, 0xb2a5705f, v37
	v_sub_f32_e32 v16, v16, v18
	v_add_f32_e32 v16, v16, v17
	v_cvt_i32_f32_e32 v38, v18
	v_exp_f32_e32 v39, v16
	global_load_dwordx4 v[16:19], v[20:21], off offset:128
	s_nop 0
	global_load_dwordx4 v[20:23], v[20:21], off offset:192
	s_nop 0
	global_load_dwordx4 v[24:27], v[28:29], off offset:128
	s_nop 0
	global_load_dwordx4 v[28:31], v[28:29], off offset:192
	s_mov_b32 s0, 0x42ce8ed0
	v_cmp_nlt_f32_e64 s[0:1], s0, v37
	v_ldexp_f32 v38, v39, v38
	s_nop 0
	v_cndmask_b32_e64 v38, 0, v38, s[0:1]
	s_mov_b32 s0, 0xc2b17218
	v_cmp_ngt_f32_e64 s[0:1], s0, v37
	s_nop 1
	v_cndmask_b32_e64 v37, v158, v38, s[0:1]
	v_add_f32_e32 v41, 1.0, v37
	v_add_f32_e32 v48, -1.0, v41
	v_frexp_mant_f32_e32 v49, v41
	v_cvt_f64_f32_e32 v[38:39], v41
	s_mov_b32 s0, 0x3f2aaaab
	v_sub_f32_e32 v50, v48, v41
	v_frexp_exp_i32_f64_e32 v38, v[38:39]
	v_cmp_gt_f32_e64 s[0:1], s0, v49
	v_sub_f32_e32 v48, v37, v48
	v_add_f32_e32 v39, 1.0, v50
	v_subbrev_co_u32_e64 v38, s[0:1], 0, v38, s[0:1]
	v_add_f32_e32 v39, v48, v39
	v_sub_u32_e32 v48, 0, v38
	v_cvt_f32_i32_e32 v38, v38
	v_ldexp_f32 v41, v41, v48
	v_ldexp_f32 v39, v39, v48
	v_add_f32_e32 v48, -1.0, v41
	v_add_f32_e32 v49, 1.0, v41
	v_add_f32_e32 v50, 1.0, v48
	v_add_f32_e32 v51, -1.0, v49
	v_sub_f32_e32 v50, v41, v50
	v_sub_f32_e32 v41, v41, v51
	v_mul_f32_e32 v51, 0x3f317218, v38
	v_add_f32_e32 v50, v39, v50
	v_add_f32_e32 v39, v39, v41
	s_mov_b32 s0, 0x3f317218
	v_fma_f32 v41, v38, s0, -v51
	v_add_f32_e32 v52, v48, v50
	v_add_f32_e32 v53, v49, v39
	v_fmac_f32_e32 v41, 0xb102e308, v38
	v_sub_f32_e32 v38, v48, v52
	v_sub_f32_e32 v48, v49, v53
	v_rcp_f32_e32 v49, v53
	v_add_f32_e32 v54, v51, v41
	v_add_f32_e32 v39, v39, v48
	v_sub_f32_e32 v48, v54, v51
	v_sub_f32_e32 v41, v41, v48
	v_mul_f32_e32 v48, v52, v49
	v_add_f32_e32 v38, v50, v38
	v_mul_f32_e32 v50, v53, v48
	v_fma_f32 v51, v48, v53, -v50
	v_fmac_f32_e32 v51, v48, v39
	v_add_f32_e32 v55, v50, v51
	v_sub_f32_e32 v56, v52, v55
	v_sub_f32_e32 v50, v55, v50
	v_sub_f32_e32 v52, v52, v56
	v_sub_f32_e32 v50, v50, v51
	v_sub_f32_e32 v51, v52, v55
	v_add_f32_e32 v38, v38, v51
	v_add_f32_e32 v38, v50, v38
	v_add_f32_e32 v50, v56, v38
	v_mul_f32_e32 v51, v49, v50
	v_sub_f32_e32 v52, v56, v50
	v_mul_f32_e32 v55, v53, v51
	v_add_f32_e32 v38, v38, v52
	v_add_f32_e32 v52, v48, v51
	v_fma_f32 v53, v51, v53, -v55
	v_sub_f32_e32 v48, v52, v48
	v_fmac_f32_e32 v53, v51, v39
	v_sub_f32_e32 v39, v51, v48
	v_add_f32_e32 v48, v55, v53
	v_sub_f32_e32 v51, v48, v55
	v_sub_f32_e32 v55, v50, v48
	v_sub_f32_e32 v50, v50, v55
	v_sub_f32_e32 v48, v50, v48
	v_sub_f32_e32 v51, v51, v53
	v_add_f32_e32 v38, v38, v48
	v_add_f32_e32 v38, v51, v38
	v_add_f32_e32 v38, v55, v38
	v_mul_f32_e32 v38, v49, v38
	v_add_f32_e32 v38, v39, v38
	v_add_f32_e32 v39, v52, v38
	v_mul_f32_e32 v48, v39, v39
	v_fmamk_f32 v51, v48, 0x3e9b6dac, v127
	v_sub_f32_e32 v49, v39, v52
	v_ldexp_f32 v50, v39, 1
	v_mul_f32_e32 v39, v39, v48
	v_fmaak_f32 v48, v48, v51, 0x3f2aaada
	v_mul_f32_e32 v39, v39, v48
	v_add_f32_e32 v48, v50, v39
	v_sub_f32_e32 v38, v38, v49
	v_sub_f32_e32 v49, v48, v50
	v_ldexp_f32 v38, v38, 1
	v_sub_f32_e32 v39, v39, v49
	v_add_f32_e32 v38, v38, v39
	v_add_f32_e32 v39, v48, v38
	v_sub_f32_e32 v48, v39, v48
	v_add_f32_e32 v49, v54, v39
	v_sub_f32_e32 v38, v38, v48
	v_sub_f32_e32 v48, v49, v54
	v_sub_f32_e32 v50, v49, v48
	v_sub_f32_e32 v39, v39, v48
	v_add_f32_e32 v48, v41, v38
	v_sub_f32_e32 v50, v54, v50
	v_sub_f32_e32 v51, v48, v41
	v_add_f32_e32 v39, v39, v50
	v_sub_f32_e32 v50, v48, v51
	v_sub_f32_e32 v38, v38, v51
	v_sub_f32_e32 v41, v41, v50
	v_add_f32_e32 v39, v48, v39
	v_add_f32_e32 v38, v38, v41
	v_add_f32_e32 v41, v49, v39
	v_sub_f32_e32 v48, v41, v49
	v_sub_f32_e32 v39, v39, v48
	v_add_f32_e32 v38, v38, v39
	s_mov_b32 s0, 0x7f800000
	v_add_f32_e32 v38, v41, v38
	v_cmp_neq_f32_e64 s[0:1], s0, v37
	v_mad_u32_u24 v51, v35, s30, v124
	s_nop 0
	v_cndmask_b32_e64 v38, v158, v38, s[0:1]
	s_mov_b32 s0, 0x33800000
	v_cmp_lt_f32_e64 s[38:39], |v37|, s0
	s_nop 1
	v_cndmask_b32_e64 v37, v38, v37, s[38:39]
	v_mul_f32_e32 v48, 0xc1000000, v37
	v_subrev_u32_e32 v37, 32, v159
	v_cmp_lt_i32_e64 s[0:1], v37, v40
	v_cmp_lt_u32_e64 s[38:39], 1, v42
	s_nop 0
	v_cndmask_b32_e64 v37, v37, v159, s[0:1]
	v_lshlrev_b32_e32 v49, 2, v37
	v_or_b32_e32 v37, v40, v35
	s_movk_i32 s0, 0x440
	v_lshl_or_b32 v50, v37, 2, v160
	v_mad_u32_u24 v37, v42, s0, v36
	v_lshlrev_b32_e32 v35, 1, v35
	v_lshl_add_u32 v36, v42, 10, v36
	v_or_b32_e32 v52, v37, v35
	v_or_b32_e32 v53, v36, v35
	s_waitcnt vmcnt(0)
	s_add_i32 s40, s31, s94
	s_cmpk_gt_i32 s40, 0x1ff
	s_cbranch_scc1 .Lstg_nopf
	s_lshl_b32 s41, s40, 7
	s_and_b32 s41, s41, 0x380
	s_ashr_i32 s42, s40, 6
	s_mul_i32 s42, s42, 0x81
	s_ashr_i32 s42, s42, 3
	s_lshl_b32 s42, s42, 4
	s_bfe_u32 s43, s40, 0x30003
	s_mul_i32 s43, s43, 0x810
	s_add_i32 s42, s42, s43
	v_and_b32_e32 v186, 15, v161
	v_lshrrev_b32_e32 v187, 4, v161
	v_lshl_add_u32 v186, v186, 3, s41
	v_lshlrev_b32_e32 v167, 2, v186
	v_add_u32_e32 v168, 0x1000, v167
	v_add_u32_e32 v169, 0x2000, v167
	v_add_u32_e32 v185, 0x3000, v167
	v_mul_u32_u24_e32 v187, 9, v187
	v_add_u32_e32 v187, s42, v187
	v_mul_u32_u24_e32 v166, 0x1c00, v187
	v_lshl_add_u32 v166, v186, 1, v166
	global_load_dwordx4 v[68:71], v167, s[64:65]
	global_load_dwordx4 v[72:75], v167, s[64:65] offset:16
	global_load_dwordx4 v[76:79], v168, s[64:65]
	global_load_dwordx4 v[80:83], v168, s[64:65] offset:16
	global_load_dwordx4 v[84:87], v169, s[64:65]
	global_load_dwordx4 v[88:91], v169, s[64:65] offset:16
	global_load_dwordx4 v[92:95], v185, s[64:65]
	global_load_dwordx4 v[96:99], v185, s[64:65] offset:16
	global_load_dwordx4 v[100:103], v167, s[66:67]
	global_load_dwordx4 v[104:107], v167, s[66:67] offset:16
	s_sub_u32 s44, s56, 0x5400
	s_subb_u32 s45, s57, 0
	global_load_dwordx4 v[108:111], v166, s[44:45]
	s_add_u32 s44, s44, 0x1c00
	s_addc_u32 s45, s45, 0
	global_load_dwordx4 v[112:115], v166, s[44:45]
	s_add_u32 s44, s44, 0x1c00
	s_addc_u32 s45, s45, 0
	global_load_dwordx4 v[116:119], v166, s[44:45]
	s_add_u32 s44, s44, 0x1c00
	s_addc_u32 s45, s45, 0
	global_load_dwordx4 v[120:123], v166, s[44:45]
	s_add_u32 s44, s44, 0x1c00
	s_addc_u32 s45, s45, 0
	global_load_dwordx4 v[128:131], v166, s[44:45]
	s_add_u32 s44, s44, 0x1c00
	s_addc_u32 s45, s45, 0
	global_load_dwordx4 v[132:135], v166, s[44:45]
	s_add_u32 s44, s44, 0x1c00
	s_addc_u32 s45, s45, 0
	global_load_dwordx4 v[136:139], v166, s[44:45]
	s_add_u32 s44, s44, 0x1c00
	s_addc_u32 s45, s45, 0
	global_load_dwordx4 v[140:143], v166, s[44:45]
	s_add_u32 s44, s44, 0x1c00
	s_addc_u32 s45, s45, 0
	global_load_dwordx4 v[144:147], v166, s[44:45]
	s_add_u32 s44, s44, 0x1c00
	s_addc_u32 s45, s45, 0
	global_load_dwordx4 v[148:151], v166, s[44:45]
	s_add_u32 s44, s44, 0x1c00
	s_addc_u32 s45, s45, 0
	global_load_dwordx4 v[152:155], v166, s[44:45]
	s_add_u32 s44, s44, 0x1c00
	s_addc_u32 s45, s45, 0
	global_load_dwordx4 v[162:165], v166, s[44:45]
	s_add_u32 s44, s56, 0xc00
	s_addc_u32 s45, s57, 0
	global_load_dwordx4 v[172:175], v166, s[44:45]
	s_add_u32 s44, s44, 0x1c00
	s_addc_u32 s45, s45, 0
	global_load_dwordx4 v[176:179], v166, s[44:45]
	s_add_u32 s44, s44, 0x1c00
	s_addc_u32 s45, s45, 0
	global_load_dwordx4 v[180:183], v166, s[44:45]
	s_add_u32 s44, s44, 0x1c00
	s_addc_u32 s45, s45, 0
	global_load_dwordx4 v[188:191], v166, s[44:45]
	s_add_u32 s44, s44, 0x1c00
	s_addc_u32 s45, s45, 0
	global_load_dwordx4 v[192:195], v166, s[44:45]
	s_add_u32 s44, s44, 0x1c00
	s_addc_u32 s45, s45, 0
	global_load_dwordx4 v[196:199], v166, s[44:45]
	s_add_u32 s44, s44, 0x1c00
	s_addc_u32 s45, s45, 0
	global_load_dwordx4 v[200:203], v166, s[44:45]
	s_add_u32 s44, s44, 0x1c00
	s_addc_u32 s45, s45, 0
	global_load_dwordx4 v[204:207], v166, s[44:45]
	s_add_u32 s44, s44, 0x1c00
	s_addc_u32 s45, s45, 0
	global_load_dwordx4 v[208:211], v166, s[44:45]
.Lstg_nopf:
.LBB0_409:
	v_add_u32_e32 v35, 0, v51
	ds_read_b128 v[36:39], v35
	ds_read_b128 v[58:61], v35 offset:64
	s_add_i32 s5, s5, 1
	v_add_u32_e32 v51, 0x1100, v51
	s_cmp_lt_i32 s5, s68
	s_waitcnt lgkmcnt(1)
	v_mfma_f32_16x16x32_bf16 v[54:57], v[36:39], v[0:3], 0
	v_mfma_f32_16x16x32_bf16 v[36:39], v[36:39], v[8:11], 0
	s_waitcnt lgkmcnt(0)
	v_mfma_f32_16x16x32_bf16 v[54:57], v[58:61], v[4:7], v[54:57]
	v_mfma_f32_16x16x32_bf16 v[36:39], v[58:61], v[12:15], v[36:39]
	ds_read_b128 v[58:61], v35 offset:128
	s_waitcnt lgkmcnt(0)
	v_mfma_f32_16x16x32_bf16 v[54:57], v[58:61], v[16:19], v[54:57]
	v_mfma_f32_16x16x32_bf16 v[36:39], v[58:61], v[24:27], v[36:39]
	ds_read_b128 v[58:61], v35 offset:192
	s_waitcnt lgkmcnt(0)
	v_mfma_f32_16x16x32_bf16 v[62:65], v[58:61], v[20:23], v[54:57]
	s_nop 3
	v_add_u32_e32 v56, 0, v53
	v_add_u32_e32 v54, 0, v52
	v_add_u32_e32 v40, 0x12100, v56
	ds_read_u16 v35, v54
	ds_read_u16 v40, v40
	v_mfma_f32_16x16x32_bf16 v[36:39], v[58:61], v[28:31], v[36:39]
	v_add_u32_e32 v52, 0x1100, v52
	v_add_u32_e32 v53, 0x1000, v53
	s_waitcnt lgkmcnt(0)
	v_lshlrev_b32_e32 v57, 16, v40
	v_add_f32_e32 v40, v45, v62
	v_mul_f32_e32 v40, 0xbfb8aa3b, v40
	v_exp_f32_e32 v40, v40
	s_nop 0
	v_add_f32_e32 v36, v46, v36
	v_mul_f32_e32 v36, 0xbfb8aa3b, v36
	v_exp_f32_e32 v36, v36
	v_add_f32_e32 v40, 1.0, v40
	v_rcp_f32_e32 v40, v40
	v_add_f32_e32 v37, v46, v37
	v_add_f32_e32 v36, 1.0, v36
	v_rcp_f32_e32 v41, v36
	v_mul_f32_e32 v36, v48, v40
	v_mul_f32_e32 v36, 0x3fb8aa3b, v36
	v_exp_f32_e32 v66, v36
	v_add_u32_e32 v40, 0x12200, v56
	ds_read_u16 v40, v40
	v_mul_f32_e32 v37, 0xbfb8aa3b, v37
	v_fma_f32 v36, -v66, v66, 1.0
	v_sqrt_f32_e32 v59, v36
	ds_read_u16 v36, v54 offset:272
	s_waitcnt lgkmcnt(1)
	v_lshlrev_b32_e32 v55, 16, v40
	v_add_f32_e32 v40, v45, v63
	v_mul_f32_e32 v40, 0xbfb8aa3b, v40
	v_exp_f32_e32 v40, v40
	v_exp_f32_e32 v37, v37
	s_waitcnt lgkmcnt(0)
	v_lshlrev_b32_e32 v36, 16, v36
	v_add_f32_e32 v38, v46, v38
	v_add_f32_e32 v40, 1.0, v40
	v_rcp_f32_e32 v58, v40
	v_add_f32_e32 v37, 1.0, v37
	v_rcp_f32_e32 v40, v37
	v_mul_f32_e32 v38, 0xbfb8aa3b, v38
	v_mul_f32_e32 v37, v48, v58
	v_mul_f32_e32 v37, 0x3fb8aa3b, v37
	v_exp_f32_e32 v63, v37
	v_exp_f32_e32 v38, v38
	v_add_f32_e32 v39, v46, v39
	v_mul_f32_e32 v39, 0xbfb8aa3b, v39
	v_fma_f32 v37, -v63, v63, 1.0
	v_sqrt_f32_e32 v58, v37
	v_lshlrev_b32_e32 v37, 16, v35
	v_pk_mul_f32 v[36:37], v[40:41], v[36:37]
	ds_read_u16 v35, v54 offset:544
	v_pk_mul_f32 v[40:41], v[36:37], v[58:59]
	v_add_f32_e32 v37, v45, v64
	v_mul_f32_e32 v37, 0xbfb8aa3b, v37
	v_exp_f32_e32 v37, v37
	v_add_f32_e32 v38, 1.0, v38
	v_rcp_f32_e32 v38, v38
	s_waitcnt lgkmcnt(0)
	v_lshlrev_b32_e32 v36, 16, v35
	v_add_f32_e32 v37, 1.0, v37
	v_rcp_f32_e32 v37, v37
	v_add_u32_e32 v35, 0x12300, v56
	ds_read_u16 v35, v35
	v_mul_f32_e32 v38, v38, v36
	v_mul_f32_e32 v37, v48, v37
	v_mul_f32_e32 v37, 0x3fb8aa3b, v37
	v_exp_f32_e32 v59, v37
	ds_read_u16 v36, v54 offset:816
	v_exp_f32_e32 v39, v39
	v_mul_f32_e32 v57, 0xbfb8aa3b, v57
	v_fma_f32 v37, -v59, v59, 1.0
	v_sqrt_f32_e32 v58, v37
	v_add_u32_e32 v37, 0x12400, v56
	ds_read_u16 v37, v37
	v_add_f32_e32 v39, 1.0, v39
	v_rcp_f32_e32 v39, v39
	s_waitcnt lgkmcnt(1)
	v_lshlrev_b32_e32 v36, 16, v36
	v_exp_f32_e32 v57, v57
	s_waitcnt lgkmcnt(0)
	v_lshlrev_b32_e32 v54, 16, v37
	v_add_f32_e32 v37, v45, v65
	v_mul_f32_e32 v37, 0xbfb8aa3b, v37
	v_exp_f32_e32 v37, v37
	v_mul_f32_e32 v62, v39, v36
	v_fma_f32 v39, v63, v41, v40
	v_mul_f32_e32 v36, v39, v59
	v_add_f32_e32 v37, 1.0, v37
	v_rcp_f32_e32 v37, v37
	v_mul_f32_e32 v40, v63, v66
	v_add_f32_e32 v57, 1.0, v57
	v_rcp_f32_e32 v57, v57
	v_mul_f32_e32 v37, v48, v37
	v_mul_f32_e32 v37, 0x3fb8aa3b, v37
	v_exp_f32_e32 v61, v37
	v_lshlrev_b32_e32 v35, 16, v35
	v_mul_f32_e32 v35, 0xbfb8aa3b, v35
	v_exp_f32_e32 v35, v35
	v_fma_f32 v37, -v61, v61, 1.0
	v_sqrt_f32_e32 v60, v37
	v_pk_fma_f32 v[36:37], v[38:39], v[58:59], v[36:37] op_sel_hi:[1,1,0]
	v_mul_f32_e32 v38, v59, v40
	v_mov_b32_e32 v63, v36
	v_pk_mul_f32 v[58:59], v[60:61], v[62:63]
	v_mul_f32_e32 v60, v61, v38
	v_add_f32_e32 v37, v58, v59
	ds_bpermute_b32 v56, v47, v60
	ds_bpermute_b32 v58, v47, v37
	v_add_f32_e32 v35, 1.0, v35
	v_rcp_f32_e32 v35, v35
	s_waitcnt lgkmcnt(1)
	v_mul_f32_e32 v56, v60, v56
	s_waitcnt lgkmcnt(0)
	v_fma_f32 v58, v60, v58, v37
	v_cndmask_b32_e32 v56, v56, v60, vcc
	v_cndmask_b32_e32 v58, v58, v37, vcc
	ds_bpermute_b32 v59, v49, v56
	ds_bpermute_b32 v61, v49, v58
	s_waitcnt lgkmcnt(1)
	v_mul_f32_e32 v59, v56, v59
	s_waitcnt lgkmcnt(0)
	v_fma_f32 v61, v56, v61, v58
	v_cndmask_b32_e64 v62, v56, v59, s[38:39]
	v_cndmask_b32_e64 v61, v58, v61, s[38:39]
	v_fmac_f32_e32 v61, v44, v62
	ds_bpermute_b32 v56, v47, v61
	ds_bpermute_b32 v58, v47, v62
	s_waitcnt lgkmcnt(1)
	v_cndmask_b32_e32 v44, v56, v44, vcc
	s_waitcnt lgkmcnt(0)
	v_cndmask_b32_e64 v56, v58, 1.0, vcc
	v_mul_f32_e32 v63, v43, v56
	v_fmac_f32_e32 v39, v40, v44
	v_mul_f32_e32 v58, v40, v63
	v_fmac_f32_e32 v37, v60, v44
	v_mul_f32_e32 v40, v60, v63
	v_fmac_f32_e32 v41, v66, v44
	v_fmac_f32_e32 v36, v38, v44
	ds_bpermute_b32 v44, v50, v61
	v_mul_f32_e32 v41, v57, v41
	v_mul_f32_e32 v59, v66, v63
	v_mul_f32_e32 v56, v38, v63
	ds_bpermute_b32 v38, v50, v62
	v_cvt_pk_bf16_f32 v41, v41, v125
	global_store_short v170, v41, s[62:63]
	v_mul_f32_e32 v41, v57, v59
	v_cvt_pk_bf16_f32 v41, v41, v125
	global_store_short v170, v41, s[90:91]
	v_mul_f32_e32 v41, 0xbfb8aa3b, v55
	v_exp_f32_e32 v41, v41
	s_nop 0
	v_add_f32_e32 v41, 1.0, v41
	v_rcp_f32_e32 v41, v41
	s_nop 0
	v_mul_f32_e32 v39, v41, v39
	v_cvt_pk_bf16_f32 v39, v39, v125
	global_store_short v170, v39, s[62:63] offset:2048
	v_mul_f32_e32 v39, v41, v58
	v_cvt_pk_bf16_f32 v39, v39, v125
	global_store_short v170, v39, s[90:91] offset:2048
	v_mul_f32_e32 v36, v35, v36
	v_cvt_pk_bf16_f32 v36, v36, v125
	global_store_short v171, v36, s[62:63]
	v_mul_f32_e32 v36, 0xbfb8aa3b, v54
	v_exp_f32_e32 v36, v36
	v_mul_f32_e32 v35, v35, v56
	v_cvt_pk_bf16_f32 v35, v35, v125
	v_add_f32_e32 v36, 1.0, v36
	v_rcp_f32_e32 v39, v36
	global_store_short v171, v35, s[90:91]
	s_waitcnt lgkmcnt(0)
	v_mul_f32_e32 v43, v43, v38
	v_mul_f32_e32 v36, v39, v37
	v_cvt_pk_bf16_f32 v41, v36, v125
	v_mul_f32_e32 v35, v39, v40
	v_add_u32_e32 v34, 16, v34
	global_store_short v171, v41, s[62:63] offset:2048
	v_cvt_pk_bf16_f32 v35, v35, v125
	global_store_short v171, v35, s[90:91] offset:2048
	v_add_u32_e32 v170, 0x8000, v170
	v_add_u32_e32 v171, 0x8000, v171
	s_cbranch_scc1 .LBB0_409
	v_cmp_eq_u32_e32 vcc, 0, v42
	s_and_saveexec_b64 s[0:1], vcc
	s_cbranch_execz .LBB0_346
	s_branch .LBB0_412
